# H/K residual-gate epilogues: 16 serialized load-wait-store pieces replaced by rolling 8-deep X prefetch with counted vmcnt; plus phase-1 load hoist
# baseline (speedup 1.0000x reference)
.LBB0_1389:
	s_waitcnt vmcnt(1)
	v_fmac_f32_e32 v36, v32, v88
	s_waitcnt vmcnt(0)
	v_fmac_f32_e32 v40, v28, v84
	v_cvt_f16_f32 v28, v36
	v_fmac_f32_e32 v37, v33, v89
	v_fmac_f32_e32 v41, v29, v85
	v_cvt_f16_f32 v29, v37
	v_and_b32_e32 v28, 0xffff, v28
	v_fmac_f32_e32 v38, v34, v90
	v_lshl_or_b32 v28, v29, 16, v28
	v_cvt_f16_f32 v29, v38
	v_fmac_f32_e32 v39, v35, v91
	v_fmac_f32_e32 v42, v30, v86
	v_cvt_f16_f32 v30, v39
	v_and_b32_e32 v29, 0xffff, v29
	v_lshl_or_b32 v29, v30, 16, v29
	v_cvt_f16_f32 v30, v40
	v_fmac_f32_e32 v43, v31, v87
	v_cvt_f16_f32 v31, v41
	v_and_b32_e32 v30, 0xffff, v30
	v_lshl_or_b32 v30, v31, 16, v30
	v_cvt_f16_f32 v31, v42
	v_cvt_f16_f32 v32, v43
	s_nop 0
	v_and_b32_e32 v31, 0xffff, v31
	v_lshl_or_b32 v31, v32, 16, v31
	global_store_dwordx4 v[52:53], v[28:31], off offset:256
.Lh_epi_exit:
	s_andn2_b64 vcc, exec, s[52:53]
	s_mov_b64 s[8:9], -1
	s_cbranch_vccnz .LBB0_1321
.LBB0_1390:
	s_cmpk_lt_u32 s68, 0x100
	s_cselect_b32 s39, 32, 8
	s_andn2_b64 vcc, exec, s[42:43]
	s_cbranch_vccnz .LBB0_1320
	s_barrier
	s_branch .LBB0_1320
.LBB0_1392:
	v_lshl_add_u64 v[194:195], v[194:195], 1, s[44:45]
	s_mov_b64 s[12:13], 0x10000
	s_mov_b64 s[16:17], 0x40000
	v_mov_b32_e32 v196, v194
	v_mov_b32_e32 v197, v195
	global_load_dwordx4 v[212:215], v[196:197], off
	global_load_dwordx4 v[216:219], v[196:197], off offset:256
	v_lshl_add_u64 v[196:197], v[196:197], 0, s[12:13]
	global_load_dwordx4 v[220:223], v[196:197], off
	global_load_dwordx4 v[224:227], v[196:197], off offset:256
	v_lshl_add_u64 v[196:197], v[196:197], 0, s[12:13]
	global_load_dwordx4 v[228:231], v[196:197], off
	global_load_dwordx4 v[232:235], v[196:197], off offset:256
	v_lshl_add_u64 v[196:197], v[196:197], 0, s[12:13]
	global_load_dwordx4 v[236:239], v[196:197], off
	global_load_dwordx4 v[240:243], v[196:197], off offset:256
	v_lshl_add_u64 v[196:197], v[196:197], 0, s[12:13]
	v_lshl_add_u64 v[196:197], v[196:197], 0, s[16:17]
	s_waitcnt vmcnt(7)
	v_cvt_f32_f16_e32 v244, v212
	v_lshrrev_b32_e32 v245, 16, v212
	v_cvt_f32_f16_e32 v246, v213
	v_lshrrev_b32_e32 v247, 16, v213
	v_cvt_f32_f16_e32 v248, v214
	v_lshrrev_b32_e32 v249, 16, v214
	v_cvt_f32_f16_e32 v250, v215
	v_lshrrev_b32_e32 v251, 16, v215
	v_cvt_f32_f16_e32 v245, v245
	v_cvt_f32_f16_e32 v247, v247
	v_cvt_f32_f16_e32 v249, v249
	v_cvt_f32_f16_e32 v251, v251
	global_load_dwordx4 v[212:215], v[196:197], off
	v_fmac_f32_e32 v244, v168, v104
	v_fmac_f32_e32 v245, v169, v105
	v_fmac_f32_e32 v246, v170, v106
	v_fmac_f32_e32 v247, v171, v107
	v_fmac_f32_e32 v248, v164, v100
	v_fmac_f32_e32 v249, v165, v101
	v_fmac_f32_e32 v250, v166, v102
	v_fmac_f32_e32 v251, v167, v103
	v_cvt_f16_f32_e32 v244, v244
	v_cvt_f16_f32_e32 v245, v245
	v_cvt_f16_f32_e32 v246, v246
	v_cvt_f16_f32_e32 v247, v247
	v_cvt_f16_f32_e32 v248, v248
	v_cvt_f16_f32_e32 v249, v249
	v_cvt_f16_f32_e32 v250, v250
	v_cvt_f16_f32_e32 v251, v251
	v_and_b32_e32 v244, 0xffff, v244
	v_lshl_or_b32 v176, v245, 16, v244
	v_and_b32_e32 v246, 0xffff, v246
	v_lshl_or_b32 v177, v247, 16, v246
	v_and_b32_e32 v248, 0xffff, v248
	v_lshl_or_b32 v178, v249, 16, v248
	v_and_b32_e32 v250, 0xffff, v250
	v_lshl_or_b32 v179, v251, 16, v250
	global_store_dwordx4 v[194:195], v[176:179], off
	s_waitcnt vmcnt(8)
	v_cvt_f32_f16_e32 v244, v216
	v_lshrrev_b32_e32 v245, 16, v216
	v_cvt_f32_f16_e32 v246, v217
	v_lshrrev_b32_e32 v247, 16, v217
	v_cvt_f32_f16_e32 v248, v218
	v_lshrrev_b32_e32 v249, 16, v218
	v_cvt_f32_f16_e32 v250, v219
	v_lshrrev_b32_e32 v251, 16, v219
	v_cvt_f32_f16_e32 v245, v245
	v_cvt_f32_f16_e32 v247, v247
	v_cvt_f32_f16_e32 v249, v249
	v_cvt_f32_f16_e32 v251, v251
	global_load_dwordx4 v[216:219], v[196:197], off offset:256
	v_lshl_add_u64 v[196:197], v[196:197], 0, s[12:13]
	v_fmac_f32_e32 v244, v160, v88
	v_fmac_f32_e32 v245, v161, v89
	v_fmac_f32_e32 v246, v162, v90
	v_fmac_f32_e32 v247, v163, v91
	v_fmac_f32_e32 v248, v156, v84
	v_fmac_f32_e32 v249, v157, v85
	v_fmac_f32_e32 v250, v158, v86
	v_fmac_f32_e32 v251, v159, v87
	v_cvt_f16_f32_e32 v244, v244
	v_cvt_f16_f32_e32 v245, v245
	v_cvt_f16_f32_e32 v246, v246
	v_cvt_f16_f32_e32 v247, v247
	v_cvt_f16_f32_e32 v248, v248
	v_cvt_f16_f32_e32 v249, v249
	v_cvt_f16_f32_e32 v250, v250
	v_cvt_f16_f32_e32 v251, v251
	v_and_b32_e32 v244, 0xffff, v244
	v_lshl_or_b32 v176, v245, 16, v244
	v_and_b32_e32 v246, 0xffff, v246
	v_lshl_or_b32 v177, v247, 16, v246
	v_and_b32_e32 v248, 0xffff, v248
	v_lshl_or_b32 v178, v249, 16, v248
	v_and_b32_e32 v250, 0xffff, v250
	v_lshl_or_b32 v179, v251, 16, v250
	global_store_dwordx4 v[194:195], v[176:179], off offset:256
	v_lshl_add_u64 v[194:195], v[194:195], 0, s[12:13]
	s_waitcnt vmcnt(9)
	v_cvt_f32_f16_e32 v244, v220
	v_lshrrev_b32_e32 v245, 16, v220
	v_cvt_f32_f16_e32 v246, v221
	v_lshrrev_b32_e32 v247, 16, v221
	v_cvt_f32_f16_e32 v248, v222
	v_lshrrev_b32_e32 v249, 16, v222
	v_cvt_f32_f16_e32 v250, v223
	v_lshrrev_b32_e32 v251, 16, v223
	v_cvt_f32_f16_e32 v245, v245
	v_cvt_f32_f16_e32 v247, v247
	v_cvt_f32_f16_e32 v249, v249
	v_cvt_f32_f16_e32 v251, v251
	global_load_dwordx4 v[220:223], v[196:197], off
	v_fmac_f32_e32 v244, v152, v104
	v_fmac_f32_e32 v245, v153, v105
	v_fmac_f32_e32 v246, v154, v106
	v_fmac_f32_e32 v247, v155, v107
	v_fmac_f32_e32 v248, v148, v100
	v_fmac_f32_e32 v249, v149, v101
	v_fmac_f32_e32 v250, v150, v102
	v_fmac_f32_e32 v251, v151, v103
	v_cvt_f16_f32_e32 v244, v244
	v_cvt_f16_f32_e32 v245, v245
	v_cvt_f16_f32_e32 v246, v246
	v_cvt_f16_f32_e32 v247, v247
	v_cvt_f16_f32_e32 v248, v248
	v_cvt_f16_f32_e32 v249, v249
	v_cvt_f16_f32_e32 v250, v250
	v_cvt_f16_f32_e32 v251, v251
	v_and_b32_e32 v244, 0xffff, v244
	v_lshl_or_b32 v176, v245, 16, v244
	v_and_b32_e32 v246, 0xffff, v246
	v_lshl_or_b32 v177, v247, 16, v246
	v_and_b32_e32 v248, 0xffff, v248
	v_lshl_or_b32 v178, v249, 16, v248
	v_and_b32_e32 v250, 0xffff, v250
	v_lshl_or_b32 v179, v251, 16, v250
	global_store_dwordx4 v[194:195], v[176:179], off
	s_waitcnt vmcnt(10)
	v_cvt_f32_f16_e32 v244, v224
	v_lshrrev_b32_e32 v245, 16, v224
	v_cvt_f32_f16_e32 v246, v225
	v_lshrrev_b32_e32 v247, 16, v225
	v_cvt_f32_f16_e32 v248, v226
	v_lshrrev_b32_e32 v249, 16, v226
	v_cvt_f32_f16_e32 v250, v227
	v_lshrrev_b32_e32 v251, 16, v227
	v_cvt_f32_f16_e32 v245, v245
	v_cvt_f32_f16_e32 v247, v247
	v_cvt_f32_f16_e32 v249, v249
	v_cvt_f32_f16_e32 v251, v251
	global_load_dwordx4 v[224:227], v[196:197], off offset:256
	v_lshl_add_u64 v[196:197], v[196:197], 0, s[12:13]
	v_fmac_f32_e32 v244, v144, v88
	v_fmac_f32_e32 v245, v145, v89
	v_fmac_f32_e32 v246, v146, v90
	v_fmac_f32_e32 v247, v147, v91
	v_fmac_f32_e32 v248, v140, v84
	v_fmac_f32_e32 v249, v141, v85
	v_fmac_f32_e32 v250, v142, v86
	v_fmac_f32_e32 v251, v143, v87
	v_cvt_f16_f32_e32 v244, v244
	v_cvt_f16_f32_e32 v245, v245
	v_cvt_f16_f32_e32 v246, v246
	v_cvt_f16_f32_e32 v247, v247
	v_cvt_f16_f32_e32 v248, v248
	v_cvt_f16_f32_e32 v249, v249
	v_cvt_f16_f32_e32 v250, v250
	v_cvt_f16_f32_e32 v251, v251
	v_and_b32_e32 v244, 0xffff, v244
	v_lshl_or_b32 v176, v245, 16, v244
	v_and_b32_e32 v246, 0xffff, v246
	v_lshl_or_b32 v177, v247, 16, v246
	v_and_b32_e32 v248, 0xffff, v248
	v_lshl_or_b32 v178, v249, 16, v248
	v_and_b32_e32 v250, 0xffff, v250
	v_lshl_or_b32 v179, v251, 16, v250
	global_store_dwordx4 v[194:195], v[176:179], off offset:256
	v_lshl_add_u64 v[194:195], v[194:195], 0, s[12:13]
	s_waitcnt vmcnt(11)
	v_cvt_f32_f16_e32 v244, v228
	v_lshrrev_b32_e32 v245, 16, v228
	v_cvt_f32_f16_e32 v246, v229
	v_lshrrev_b32_e32 v247, 16, v229
	v_cvt_f32_f16_e32 v248, v230
	v_lshrrev_b32_e32 v249, 16, v230
	v_cvt_f32_f16_e32 v250, v231
	v_lshrrev_b32_e32 v251, 16, v231
	v_cvt_f32_f16_e32 v245, v245
	v_cvt_f32_f16_e32 v247, v247
	v_cvt_f32_f16_e32 v249, v249
	v_cvt_f32_f16_e32 v251, v251
	global_load_dwordx4 v[228:231], v[196:197], off
	v_fmac_f32_e32 v244, v136, v104
	v_fmac_f32_e32 v245, v137, v105
	v_fmac_f32_e32 v246, v138, v106
	v_fmac_f32_e32 v247, v139, v107
	v_fmac_f32_e32 v248, v132, v100
	v_fmac_f32_e32 v249, v133, v101
	v_fmac_f32_e32 v250, v134, v102
	v_fmac_f32_e32 v251, v135, v103
	v_cvt_f16_f32_e32 v244, v244
	v_cvt_f16_f32_e32 v245, v245
	v_cvt_f16_f32_e32 v246, v246
	v_cvt_f16_f32_e32 v247, v247
	v_cvt_f16_f32_e32 v248, v248
	v_cvt_f16_f32_e32 v249, v249
	v_cvt_f16_f32_e32 v250, v250
	v_cvt_f16_f32_e32 v251, v251
	v_and_b32_e32 v244, 0xffff, v244
	v_lshl_or_b32 v176, v245, 16, v244
	v_and_b32_e32 v246, 0xffff, v246
	v_lshl_or_b32 v177, v247, 16, v246
	v_and_b32_e32 v248, 0xffff, v248
	v_lshl_or_b32 v178, v249, 16, v248
	v_and_b32_e32 v250, 0xffff, v250
	v_lshl_or_b32 v179, v251, 16, v250
	global_store_dwordx4 v[194:195], v[176:179], off
	s_waitcnt vmcnt(12)
	v_cvt_f32_f16_e32 v244, v232
	v_lshrrev_b32_e32 v245, 16, v232
	v_cvt_f32_f16_e32 v246, v233
	v_lshrrev_b32_e32 v247, 16, v233
	v_cvt_f32_f16_e32 v248, v234
	v_lshrrev_b32_e32 v249, 16, v234
	v_cvt_f32_f16_e32 v250, v235
	v_lshrrev_b32_e32 v251, 16, v235
	v_cvt_f32_f16_e32 v245, v245
	v_cvt_f32_f16_e32 v247, v247
	v_cvt_f32_f16_e32 v249, v249
	v_cvt_f32_f16_e32 v251, v251
	global_load_dwordx4 v[232:235], v[196:197], off offset:256
	v_lshl_add_u64 v[196:197], v[196:197], 0, s[12:13]
	v_fmac_f32_e32 v244, v128, v88
	v_fmac_f32_e32 v245, v129, v89
	v_fmac_f32_e32 v246, v130, v90
	v_fmac_f32_e32 v247, v131, v91
	v_fmac_f32_e32 v248, v124, v84
	v_fmac_f32_e32 v249, v125, v85
	v_fmac_f32_e32 v250, v126, v86
	v_fmac_f32_e32 v251, v127, v87
	v_cvt_f16_f32_e32 v244, v244
	v_cvt_f16_f32_e32 v245, v245
	v_cvt_f16_f32_e32 v246, v246
	v_cvt_f16_f32_e32 v247, v247
	v_cvt_f16_f32_e32 v248, v248
	v_cvt_f16_f32_e32 v249, v249
	v_cvt_f16_f32_e32 v250, v250
	v_cvt_f16_f32_e32 v251, v251
	v_and_b32_e32 v244, 0xffff, v244
	v_lshl_or_b32 v176, v245, 16, v244
	v_and_b32_e32 v246, 0xffff, v246
	v_lshl_or_b32 v177, v247, 16, v246
	v_and_b32_e32 v248, 0xffff, v248
	v_lshl_or_b32 v178, v249, 16, v248
	v_and_b32_e32 v250, 0xffff, v250
	v_lshl_or_b32 v179, v251, 16, v250
	global_store_dwordx4 v[194:195], v[176:179], off offset:256
	v_lshl_add_u64 v[194:195], v[194:195], 0, s[12:13]
	s_waitcnt vmcnt(13)
	v_cvt_f32_f16_e32 v244, v236
	v_lshrrev_b32_e32 v245, 16, v236
	v_cvt_f32_f16_e32 v246, v237
	v_lshrrev_b32_e32 v247, 16, v237
	v_cvt_f32_f16_e32 v248, v238
	v_lshrrev_b32_e32 v249, 16, v238
	v_cvt_f32_f16_e32 v250, v239
	v_lshrrev_b32_e32 v251, 16, v239
	v_cvt_f32_f16_e32 v245, v245
	v_cvt_f32_f16_e32 v247, v247
	v_cvt_f32_f16_e32 v249, v249
	v_cvt_f32_f16_e32 v251, v251
	global_load_dwordx4 v[236:239], v[196:197], off
	v_fmac_f32_e32 v244, v120, v104
	v_fmac_f32_e32 v245, v121, v105
	v_fmac_f32_e32 v246, v122, v106
	v_fmac_f32_e32 v247, v123, v107
	v_fmac_f32_e32 v248, v116, v100
	v_fmac_f32_e32 v249, v117, v101
	v_fmac_f32_e32 v250, v118, v102
	v_fmac_f32_e32 v251, v119, v103
	v_cvt_f16_f32_e32 v244, v244
	v_cvt_f16_f32_e32 v245, v245
	v_cvt_f16_f32_e32 v246, v246
	v_cvt_f16_f32_e32 v247, v247
	v_cvt_f16_f32_e32 v248, v248
	v_cvt_f16_f32_e32 v249, v249
	v_cvt_f16_f32_e32 v250, v250
	v_cvt_f16_f32_e32 v251, v251
	v_and_b32_e32 v244, 0xffff, v244
	v_lshl_or_b32 v176, v245, 16, v244
	v_and_b32_e32 v246, 0xffff, v246
	v_lshl_or_b32 v177, v247, 16, v246
	v_and_b32_e32 v248, 0xffff, v248
	v_lshl_or_b32 v178, v249, 16, v248
	v_and_b32_e32 v250, 0xffff, v250
	v_lshl_or_b32 v179, v251, 16, v250
	global_store_dwordx4 v[194:195], v[176:179], off
	s_waitcnt vmcnt(14)
	v_cvt_f32_f16_e32 v244, v240
	v_lshrrev_b32_e32 v245, 16, v240
	v_cvt_f32_f16_e32 v246, v241
	v_lshrrev_b32_e32 v247, 16, v241
	v_cvt_f32_f16_e32 v248, v242
	v_lshrrev_b32_e32 v249, 16, v242
	v_cvt_f32_f16_e32 v250, v243
	v_lshrrev_b32_e32 v251, 16, v243
	v_cvt_f32_f16_e32 v245, v245
	v_cvt_f32_f16_e32 v247, v247
	v_cvt_f32_f16_e32 v249, v249
	v_cvt_f32_f16_e32 v251, v251
	global_load_dwordx4 v[240:243], v[196:197], off offset:256
	v_lshl_add_u64 v[196:197], v[196:197], 0, s[12:13]
	v_fmac_f32_e32 v244, v112, v88
	v_fmac_f32_e32 v245, v113, v89
	v_fmac_f32_e32 v246, v114, v90
	v_fmac_f32_e32 v247, v115, v91
	v_fmac_f32_e32 v248, v108, v84
	v_fmac_f32_e32 v249, v109, v85
	v_fmac_f32_e32 v250, v110, v86
	v_fmac_f32_e32 v251, v111, v87
	v_cvt_f16_f32_e32 v244, v244
	v_cvt_f16_f32_e32 v245, v245
	v_cvt_f16_f32_e32 v246, v246
	v_cvt_f16_f32_e32 v247, v247
	v_cvt_f16_f32_e32 v248, v248
	v_cvt_f16_f32_e32 v249, v249
	v_cvt_f16_f32_e32 v250, v250
	v_cvt_f16_f32_e32 v251, v251
	v_and_b32_e32 v244, 0xffff, v244
	v_lshl_or_b32 v176, v245, 16, v244
	v_and_b32_e32 v246, 0xffff, v246
	v_lshl_or_b32 v177, v247, 16, v246
	v_and_b32_e32 v248, 0xffff, v248
	v_lshl_or_b32 v178, v249, 16, v248
	v_and_b32_e32 v250, 0xffff, v250
	v_lshl_or_b32 v179, v251, 16, v250
	global_store_dwordx4 v[194:195], v[176:179], off offset:256
	v_lshl_add_u64 v[194:195], v[194:195], 0, s[12:13]
	v_lshl_add_u64 v[194:195], v[194:195], 0, s[16:17]
	s_waitcnt vmcnt(15)
	v_cvt_f32_f16_e32 v244, v212
	v_lshrrev_b32_e32 v245, 16, v212
	v_cvt_f32_f16_e32 v246, v213
	v_lshrrev_b32_e32 v247, 16, v213
	v_cvt_f32_f16_e32 v248, v214
	v_lshrrev_b32_e32 v249, 16, v214
	v_cvt_f32_f16_e32 v250, v215
	v_lshrrev_b32_e32 v251, 16, v215
	v_cvt_f32_f16_e32 v245, v245
	v_cvt_f32_f16_e32 v247, v247
	v_cvt_f32_f16_e32 v249, v249
	v_cvt_f32_f16_e32 v251, v251
	v_fmac_f32_e32 v244, v96, v104
	v_fmac_f32_e32 v245, v97, v105
	v_fmac_f32_e32 v246, v98, v106
	v_fmac_f32_e32 v247, v99, v107
	v_fmac_f32_e32 v248, v92, v100
	v_fmac_f32_e32 v249, v93, v101
	v_fmac_f32_e32 v250, v94, v102
	v_fmac_f32_e32 v251, v95, v103
	v_cvt_f16_f32_e32 v244, v244
	v_cvt_f16_f32_e32 v245, v245
	v_cvt_f16_f32_e32 v246, v246
	v_cvt_f16_f32_e32 v247, v247
	v_cvt_f16_f32_e32 v248, v248
	v_cvt_f16_f32_e32 v249, v249
	v_cvt_f16_f32_e32 v250, v250
	v_cvt_f16_f32_e32 v251, v251
	v_and_b32_e32 v244, 0xffff, v244
	v_lshl_or_b32 v176, v245, 16, v244
	v_and_b32_e32 v246, 0xffff, v246
	v_lshl_or_b32 v177, v247, 16, v246
	v_and_b32_e32 v248, 0xffff, v248
	v_lshl_or_b32 v178, v249, 16, v248
	v_and_b32_e32 v250, 0xffff, v250
	v_lshl_or_b32 v179, v251, 16, v250
	global_store_dwordx4 v[194:195], v[176:179], off
	s_waitcnt vmcnt(14)
	v_cvt_f32_f16_e32 v244, v216
	v_lshrrev_b32_e32 v245, 16, v216
	v_cvt_f32_f16_e32 v246, v217
	v_lshrrev_b32_e32 v247, 16, v217
	v_cvt_f32_f16_e32 v248, v218
	v_lshrrev_b32_e32 v249, 16, v218
	v_cvt_f32_f16_e32 v250, v219
	v_lshrrev_b32_e32 v251, 16, v219
	v_cvt_f32_f16_e32 v245, v245
	v_cvt_f32_f16_e32 v247, v247
	v_cvt_f32_f16_e32 v249, v249
	v_cvt_f32_f16_e32 v251, v251
	v_fmac_f32_e32 v244, v80, v88
	v_fmac_f32_e32 v245, v81, v89
	v_fmac_f32_e32 v246, v82, v90
	v_fmac_f32_e32 v247, v83, v91
	v_fmac_f32_e32 v248, v76, v84
	v_fmac_f32_e32 v249, v77, v85
	v_fmac_f32_e32 v250, v78, v86
	v_fmac_f32_e32 v251, v79, v87
	v_cvt_f16_f32_e32 v244, v244
	v_cvt_f16_f32_e32 v245, v245
	v_cvt_f16_f32_e32 v246, v246
	v_cvt_f16_f32_e32 v247, v247
	v_cvt_f16_f32_e32 v248, v248
	v_cvt_f16_f32_e32 v249, v249
	v_cvt_f16_f32_e32 v250, v250
	v_cvt_f16_f32_e32 v251, v251
	v_and_b32_e32 v244, 0xffff, v244
	v_lshl_or_b32 v176, v245, 16, v244
	v_and_b32_e32 v246, 0xffff, v246
	v_lshl_or_b32 v177, v247, 16, v246
	v_and_b32_e32 v248, 0xffff, v248
	v_lshl_or_b32 v178, v249, 16, v248
	v_and_b32_e32 v250, 0xffff, v250
	v_lshl_or_b32 v179, v251, 16, v250
	global_store_dwordx4 v[194:195], v[176:179], off offset:256
	v_lshl_add_u64 v[194:195], v[194:195], 0, s[12:13]
	s_waitcnt vmcnt(13)
	v_cvt_f32_f16_e32 v244, v220
	v_lshrrev_b32_e32 v245, 16, v220
	v_cvt_f32_f16_e32 v246, v221
	v_lshrrev_b32_e32 v247, 16, v221
	v_cvt_f32_f16_e32 v248, v222
	v_lshrrev_b32_e32 v249, 16, v222
	v_cvt_f32_f16_e32 v250, v223
	v_lshrrev_b32_e32 v251, 16, v223
	v_cvt_f32_f16_e32 v245, v245
	v_cvt_f32_f16_e32 v247, v247
	v_cvt_f32_f16_e32 v249, v249
	v_cvt_f32_f16_e32 v251, v251
	v_fmac_f32_e32 v244, v72, v104
	v_fmac_f32_e32 v245, v73, v105
	v_fmac_f32_e32 v246, v74, v106
	v_fmac_f32_e32 v247, v75, v107
	v_fmac_f32_e32 v248, v68, v100
	v_fmac_f32_e32 v249, v69, v101
	v_fmac_f32_e32 v250, v70, v102
	v_fmac_f32_e32 v251, v71, v103
	v_cvt_f16_f32_e32 v244, v244
	v_cvt_f16_f32_e32 v245, v245
	v_cvt_f16_f32_e32 v246, v246
	v_cvt_f16_f32_e32 v247, v247
	v_cvt_f16_f32_e32 v248, v248
	v_cvt_f16_f32_e32 v249, v249
	v_cvt_f16_f32_e32 v250, v250
	v_cvt_f16_f32_e32 v251, v251
	v_and_b32_e32 v244, 0xffff, v244
	v_lshl_or_b32 v176, v245, 16, v244
	v_and_b32_e32 v246, 0xffff, v246
	v_lshl_or_b32 v177, v247, 16, v246
	v_and_b32_e32 v248, 0xffff, v248
	v_lshl_or_b32 v178, v249, 16, v248
	v_and_b32_e32 v250, 0xffff, v250
	v_lshl_or_b32 v179, v251, 16, v250
	global_store_dwordx4 v[194:195], v[176:179], off
	s_waitcnt vmcnt(12)
	v_cvt_f32_f16_e32 v244, v224
	v_lshrrev_b32_e32 v245, 16, v224
	v_cvt_f32_f16_e32 v246, v225
	v_lshrrev_b32_e32 v247, 16, v225
	v_cvt_f32_f16_e32 v248, v226
	v_lshrrev_b32_e32 v249, 16, v226
	v_cvt_f32_f16_e32 v250, v227
	v_lshrrev_b32_e32 v251, 16, v227
	v_cvt_f32_f16_e32 v245, v245
	v_cvt_f32_f16_e32 v247, v247
	v_cvt_f32_f16_e32 v249, v249
	v_cvt_f32_f16_e32 v251, v251
	v_fmac_f32_e32 v244, v64, v88
	v_fmac_f32_e32 v245, v65, v89
	v_fmac_f32_e32 v246, v66, v90
	v_fmac_f32_e32 v247, v67, v91
	v_fmac_f32_e32 v248, v60, v84
	v_fmac_f32_e32 v249, v61, v85
	v_fmac_f32_e32 v250, v62, v86
	v_fmac_f32_e32 v251, v63, v87
	v_cvt_f16_f32_e32 v244, v244
	v_cvt_f16_f32_e32 v245, v245
	v_cvt_f16_f32_e32 v246, v246
	v_cvt_f16_f32_e32 v247, v247
	v_cvt_f16_f32_e32 v248, v248
	v_cvt_f16_f32_e32 v249, v249
	v_cvt_f16_f32_e32 v250, v250
	v_cvt_f16_f32_e32 v251, v251
	v_and_b32_e32 v244, 0xffff, v244
	v_lshl_or_b32 v176, v245, 16, v244
	v_and_b32_e32 v246, 0xffff, v246
	v_lshl_or_b32 v177, v247, 16, v246
	v_and_b32_e32 v248, 0xffff, v248
	v_lshl_or_b32 v178, v249, 16, v248
	v_and_b32_e32 v250, 0xffff, v250
	v_lshl_or_b32 v179, v251, 16, v250
	global_store_dwordx4 v[194:195], v[176:179], off offset:256
	v_lshl_add_u64 v[194:195], v[194:195], 0, s[12:13]
	s_waitcnt vmcnt(11)
	v_cvt_f32_f16_e32 v244, v228
	v_lshrrev_b32_e32 v245, 16, v228
	v_cvt_f32_f16_e32 v246, v229
	v_lshrrev_b32_e32 v247, 16, v229
	v_cvt_f32_f16_e32 v248, v230
	v_lshrrev_b32_e32 v249, 16, v230
	v_cvt_f32_f16_e32 v250, v231
	v_lshrrev_b32_e32 v251, 16, v231
	v_cvt_f32_f16_e32 v245, v245
	v_cvt_f32_f16_e32 v247, v247
	v_cvt_f32_f16_e32 v249, v249
	v_cvt_f32_f16_e32 v251, v251
	v_fmac_f32_e32 v244, v56, v104
	v_fmac_f32_e32 v245, v57, v105
	v_fmac_f32_e32 v246, v58, v106
	v_fmac_f32_e32 v247, v59, v107
	v_fmac_f32_e32 v248, v52, v100
	v_fmac_f32_e32 v249, v53, v101
	v_fmac_f32_e32 v250, v54, v102
	v_fmac_f32_e32 v251, v55, v103
	v_cvt_f16_f32_e32 v244, v244
	v_cvt_f16_f32_e32 v245, v245
	v_cvt_f16_f32_e32 v246, v246
	v_cvt_f16_f32_e32 v247, v247
	v_cvt_f16_f32_e32 v248, v248
	v_cvt_f16_f32_e32 v249, v249
	v_cvt_f16_f32_e32 v250, v250
	v_cvt_f16_f32_e32 v251, v251
	v_and_b32_e32 v244, 0xffff, v244
	v_lshl_or_b32 v176, v245, 16, v244
	v_and_b32_e32 v246, 0xffff, v246
	v_lshl_or_b32 v177, v247, 16, v246
	v_and_b32_e32 v248, 0xffff, v248
	v_lshl_or_b32 v178, v249, 16, v248
	v_and_b32_e32 v250, 0xffff, v250
	v_lshl_or_b32 v179, v251, 16, v250
	global_store_dwordx4 v[194:195], v[176:179], off
	s_waitcnt vmcnt(10)
	v_cvt_f32_f16_e32 v244, v232
	v_lshrrev_b32_e32 v245, 16, v232
	v_cvt_f32_f16_e32 v246, v233
	v_lshrrev_b32_e32 v247, 16, v233
	v_cvt_f32_f16_e32 v248, v234
	v_lshrrev_b32_e32 v249, 16, v234
	v_cvt_f32_f16_e32 v250, v235
	v_lshrrev_b32_e32 v251, 16, v235
	v_cvt_f32_f16_e32 v245, v245
	v_cvt_f32_f16_e32 v247, v247
	v_cvt_f32_f16_e32 v249, v249
	v_cvt_f32_f16_e32 v251, v251
	v_fmac_f32_e32 v244, v48, v88
	v_fmac_f32_e32 v245, v49, v89
	v_fmac_f32_e32 v246, v50, v90
	v_fmac_f32_e32 v247, v51, v91
	v_fmac_f32_e32 v248, v44, v84
	v_fmac_f32_e32 v249, v45, v85
	v_fmac_f32_e32 v250, v46, v86
	v_fmac_f32_e32 v251, v47, v87
	v_cvt_f16_f32_e32 v244, v244
	v_cvt_f16_f32_e32 v245, v245
	v_cvt_f16_f32_e32 v246, v246
	v_cvt_f16_f32_e32 v247, v247
	v_cvt_f16_f32_e32 v248, v248
	v_cvt_f16_f32_e32 v249, v249
	v_cvt_f16_f32_e32 v250, v250
	v_cvt_f16_f32_e32 v251, v251
	v_and_b32_e32 v244, 0xffff, v244
	v_lshl_or_b32 v176, v245, 16, v244
	v_and_b32_e32 v246, 0xffff, v246
	v_lshl_or_b32 v177, v247, 16, v246
	v_and_b32_e32 v248, 0xffff, v248
	v_lshl_or_b32 v178, v249, 16, v248
	v_and_b32_e32 v250, 0xffff, v250
	v_lshl_or_b32 v179, v251, 16, v250
	global_store_dwordx4 v[194:195], v[176:179], off offset:256
	v_lshl_add_u64 v[194:195], v[194:195], 0, s[12:13]
	s_waitcnt vmcnt(9)
	v_cvt_f32_f16_e32 v244, v236
	v_lshrrev_b32_e32 v245, 16, v236
	v_cvt_f32_f16_e32 v246, v237
	v_lshrrev_b32_e32 v247, 16, v237
	v_cvt_f32_f16_e32 v248, v238
	v_lshrrev_b32_e32 v249, 16, v238
	v_cvt_f32_f16_e32 v250, v239
	v_lshrrev_b32_e32 v251, 16, v239
	v_cvt_f32_f16_e32 v245, v245
	v_cvt_f32_f16_e32 v247, v247
	v_cvt_f32_f16_e32 v249, v249
	v_cvt_f32_f16_e32 v251, v251
	v_fmac_f32_e32 v244, v40, v104
	v_fmac_f32_e32 v245, v41, v105
	v_fmac_f32_e32 v246, v42, v106
	v_fmac_f32_e32 v247, v43, v107
	v_fmac_f32_e32 v248, v36, v100
	v_fmac_f32_e32 v249, v37, v101
	v_fmac_f32_e32 v250, v38, v102
	v_fmac_f32_e32 v251, v39, v103
	v_cvt_f16_f32_e32 v244, v244
	v_cvt_f16_f32_e32 v245, v245
	v_cvt_f16_f32_e32 v246, v246
	v_cvt_f16_f32_e32 v247, v247
	v_cvt_f16_f32_e32 v248, v248
	v_cvt_f16_f32_e32 v249, v249
	v_cvt_f16_f32_e32 v250, v250
	v_cvt_f16_f32_e32 v251, v251
	v_and_b32_e32 v244, 0xffff, v244
	v_lshl_or_b32 v176, v245, 16, v244
	v_and_b32_e32 v246, 0xffff, v246
	v_lshl_or_b32 v177, v247, 16, v246
	v_and_b32_e32 v248, 0xffff, v248
	v_lshl_or_b32 v178, v249, 16, v248
	v_and_b32_e32 v250, 0xffff, v250
	v_lshl_or_b32 v179, v251, 16, v250
	global_store_dwordx4 v[194:195], v[176:179], off
	s_waitcnt vmcnt(8)
	v_cvt_f32_f16_e32 v244, v240
	v_lshrrev_b32_e32 v245, 16, v240
	v_cvt_f32_f16_e32 v246, v241
	v_lshrrev_b32_e32 v247, 16, v241
	v_cvt_f32_f16_e32 v248, v242
	v_lshrrev_b32_e32 v249, 16, v242
	v_cvt_f32_f16_e32 v250, v243
	v_lshrrev_b32_e32 v251, 16, v243
	v_cvt_f32_f16_e32 v245, v245
	v_cvt_f32_f16_e32 v247, v247
	v_cvt_f32_f16_e32 v249, v249
	v_cvt_f32_f16_e32 v251, v251
	v_fmac_f32_e32 v244, v32, v88
	v_fmac_f32_e32 v245, v33, v89
	v_fmac_f32_e32 v246, v34, v90
	v_fmac_f32_e32 v247, v35, v91
	v_fmac_f32_e32 v248, v28, v84
	v_fmac_f32_e32 v249, v29, v85
	v_fmac_f32_e32 v250, v30, v86
	v_fmac_f32_e32 v251, v31, v87
	v_cvt_f16_f32_e32 v244, v244
	v_cvt_f16_f32_e32 v245, v245
	v_cvt_f16_f32_e32 v246, v246
	v_cvt_f16_f32_e32 v247, v247
	v_cvt_f16_f32_e32 v248, v248
	v_cvt_f16_f32_e32 v249, v249
	v_cvt_f16_f32_e32 v250, v250
	v_cvt_f16_f32_e32 v251, v251
	v_and_b32_e32 v244, 0xffff, v244
	v_lshl_or_b32 v176, v245, 16, v244
	v_and_b32_e32 v246, 0xffff, v246
	v_lshl_or_b32 v177, v247, 16, v246
	v_and_b32_e32 v248, 0xffff, v248
	v_lshl_or_b32 v178, v249, 16, v248
	v_and_b32_e32 v250, 0xffff, v250
	v_lshl_or_b32 v179, v251, 16, v250
	global_store_dwordx4 v[194:195], v[176:179], off offset:256
	s_branch .Lh_epi_exit

.LBB0_1706:
	s_cmp_lt_i32 s68, 64
	s_movk_i32 s8, 0x6000
	s_cselect_b32 s8, 0x3000, s8
	s_lshl_b32 s9, s69, 8
	s_lshl_b32 s12, s68, 8
	s_or_b32 s9, s9, s59
	s_cmp_gt_i32 s68, 31
	s_cselect_b32 s8, s8, 0
	s_lshl_b32 s8, s8, 2
	s_add_u32 s8, s37, s8
	v_lshl_add_u32 v190, v60, 3, s9
	s_addc_u32 s9, s43, 0
	s_add_i32 s12, s12, s58
	v_add_u32_e32 v182, s12, v182
	v_ashrrev_i32_e32 v183, 31, v182
	v_lshlrev_b64 v[182:183], 12, v[182:183]
	v_ashrrev_i32_e32 v191, 31, v190
	v_lshl_add_u64 v[182:183], s[48:49], 0, v[182:183]
	v_lshl_add_u64 v[64:65], v[190:191], 2, s[8:9]
	v_lshl_add_u64 v[182:183], v[190:191], 1, v[182:183]
	global_load_dwordx4 v[68:71], v[64:65], off offset:16
	global_load_dwordx4 v[72:75], v[64:65], off
	global_load_dwordx4 v[60:63], v[64:65], off offset:528
	s_nop 0
	global_load_dwordx4 v[64:67], v[64:65], off offset:512
	s_mov_b64 s[8:9], 0x20000
	s_mov_b64 s[12:13], 0x10000
	s_mov_b64 s[16:17], 0x40000
	v_mov_b32_e32 v194, v182
	v_mov_b32_e32 v195, v183
	global_load_dwordx4 v[212:215], v[194:195], off
	global_load_dwordx4 v[216:219], v[194:195], off offset:256
	v_lshl_add_u64 v[194:195], v[194:195], 0, s[12:13]
	global_load_dwordx4 v[220:223], v[194:195], off
	global_load_dwordx4 v[224:227], v[194:195], off offset:256
	v_lshl_add_u64 v[194:195], v[194:195], 0, s[12:13]
	global_load_dwordx4 v[228:231], v[194:195], off
	global_load_dwordx4 v[232:235], v[194:195], off offset:256
	v_lshl_add_u64 v[194:195], v[194:195], 0, s[12:13]
	global_load_dwordx4 v[236:239], v[194:195], off
	global_load_dwordx4 v[240:243], v[194:195], off offset:256
	v_lshl_add_u64 v[194:195], v[194:195], 0, s[12:13]
	v_lshl_add_u64 v[194:195], v[194:195], 0, s[16:17]
	s_waitcnt vmcnt(7)
	v_cvt_f32_f16_e32 v244, v212
	v_lshrrev_b32_e32 v245, 16, v212
	v_cvt_f32_f16_e32 v246, v213
	v_lshrrev_b32_e32 v247, 16, v213
	v_cvt_f32_f16_e32 v248, v214
	v_lshrrev_b32_e32 v249, 16, v214
	v_cvt_f32_f16_e32 v250, v215
	v_lshrrev_b32_e32 v251, 16, v215
	v_cvt_f32_f16_e32 v245, v245
	v_cvt_f32_f16_e32 v247, v247
	v_cvt_f32_f16_e32 v249, v249
	v_cvt_f32_f16_e32 v251, v251
	global_load_dwordx4 v[212:215], v[194:195], off
	v_fmac_f32_e32 v244, v168, v72
	v_fmac_f32_e32 v245, v169, v73
	v_fmac_f32_e32 v246, v170, v74
	v_fmac_f32_e32 v247, v171, v75
	v_fmac_f32_e32 v248, v164, v68
	v_fmac_f32_e32 v249, v165, v69
	v_fmac_f32_e32 v250, v166, v70
	v_fmac_f32_e32 v251, v167, v71
	v_cvt_f16_f32_e32 v244, v244
	v_cvt_f16_f32_e32 v245, v245
	v_cvt_f16_f32_e32 v246, v246
	v_cvt_f16_f32_e32 v247, v247
	v_cvt_f16_f32_e32 v248, v248
	v_cvt_f16_f32_e32 v249, v249
	v_cvt_f16_f32_e32 v250, v250
	v_cvt_f16_f32_e32 v251, v251
	v_and_b32_e32 v244, 0xffff, v244
	v_lshl_or_b32 v204, v245, 16, v244
	v_and_b32_e32 v246, 0xffff, v246
	v_lshl_or_b32 v205, v247, 16, v246
	v_and_b32_e32 v248, 0xffff, v248
	v_lshl_or_b32 v206, v249, 16, v248
	v_and_b32_e32 v250, 0xffff, v250
	v_lshl_or_b32 v207, v251, 16, v250
	global_store_dwordx4 v[182:183], v[204:207], off
	s_waitcnt vmcnt(8)
	v_cvt_f32_f16_e32 v244, v216
	v_lshrrev_b32_e32 v245, 16, v216
	v_cvt_f32_f16_e32 v246, v217
	v_lshrrev_b32_e32 v247, 16, v217
	v_cvt_f32_f16_e32 v248, v218
	v_lshrrev_b32_e32 v249, 16, v218
	v_cvt_f32_f16_e32 v250, v219
	v_lshrrev_b32_e32 v251, 16, v219
	v_cvt_f32_f16_e32 v245, v245
	v_cvt_f32_f16_e32 v247, v247
	v_cvt_f32_f16_e32 v249, v249
	v_cvt_f32_f16_e32 v251, v251
	global_load_dwordx4 v[216:219], v[194:195], off offset:256
	v_lshl_add_u64 v[194:195], v[194:195], 0, s[12:13]
	v_fmac_f32_e32 v244, v160, v64
	v_fmac_f32_e32 v245, v161, v65
	v_fmac_f32_e32 v246, v162, v66
	v_fmac_f32_e32 v247, v163, v67
	v_fmac_f32_e32 v248, v156, v60
	v_fmac_f32_e32 v249, v157, v61
	v_fmac_f32_e32 v250, v158, v62
	v_fmac_f32_e32 v251, v159, v63
	v_cvt_f16_f32_e32 v244, v244
	v_cvt_f16_f32_e32 v245, v245
	v_cvt_f16_f32_e32 v246, v246
	v_cvt_f16_f32_e32 v247, v247
	v_cvt_f16_f32_e32 v248, v248
	v_cvt_f16_f32_e32 v249, v249
	v_cvt_f16_f32_e32 v250, v250
	v_cvt_f16_f32_e32 v251, v251
	v_and_b32_e32 v244, 0xffff, v244
	v_lshl_or_b32 v204, v245, 16, v244
	v_and_b32_e32 v246, 0xffff, v246
	v_lshl_or_b32 v205, v247, 16, v246
	v_and_b32_e32 v248, 0xffff, v248
	v_lshl_or_b32 v206, v249, 16, v248
	v_and_b32_e32 v250, 0xffff, v250
	v_lshl_or_b32 v207, v251, 16, v250
	global_store_dwordx4 v[182:183], v[204:207], off offset:256
	v_lshl_add_u64 v[182:183], v[182:183], 0, s[12:13]
	s_waitcnt vmcnt(9)
	v_cvt_f32_f16_e32 v244, v220
	v_lshrrev_b32_e32 v245, 16, v220
	v_cvt_f32_f16_e32 v246, v221
	v_lshrrev_b32_e32 v247, 16, v221
	v_cvt_f32_f16_e32 v248, v222
	v_lshrrev_b32_e32 v249, 16, v222
	v_cvt_f32_f16_e32 v250, v223
	v_lshrrev_b32_e32 v251, 16, v223
	v_cvt_f32_f16_e32 v245, v245
	v_cvt_f32_f16_e32 v247, v247
	v_cvt_f32_f16_e32 v249, v249
	v_cvt_f32_f16_e32 v251, v251
	global_load_dwordx4 v[220:223], v[194:195], off
	v_fmac_f32_e32 v244, v152, v72
	v_fmac_f32_e32 v245, v153, v73
	v_fmac_f32_e32 v246, v154, v74
	v_fmac_f32_e32 v247, v155, v75
	v_fmac_f32_e32 v248, v148, v68
	v_fmac_f32_e32 v249, v149, v69
	v_fmac_f32_e32 v250, v150, v70
	v_fmac_f32_e32 v251, v151, v71
	v_cvt_f16_f32_e32 v244, v244
	v_cvt_f16_f32_e32 v245, v245
	v_cvt_f16_f32_e32 v246, v246
	v_cvt_f16_f32_e32 v247, v247
	v_cvt_f16_f32_e32 v248, v248
	v_cvt_f16_f32_e32 v249, v249
	v_cvt_f16_f32_e32 v250, v250
	v_cvt_f16_f32_e32 v251, v251
	v_and_b32_e32 v244, 0xffff, v244
	v_lshl_or_b32 v204, v245, 16, v244
	v_and_b32_e32 v246, 0xffff, v246
	v_lshl_or_b32 v205, v247, 16, v246
	v_and_b32_e32 v248, 0xffff, v248
	v_lshl_or_b32 v206, v249, 16, v248
	v_and_b32_e32 v250, 0xffff, v250
	v_lshl_or_b32 v207, v251, 16, v250
	global_store_dwordx4 v[182:183], v[204:207], off
	s_waitcnt vmcnt(10)
	v_cvt_f32_f16_e32 v244, v224
	v_lshrrev_b32_e32 v245, 16, v224
	v_cvt_f32_f16_e32 v246, v225
	v_lshrrev_b32_e32 v247, 16, v225
	v_cvt_f32_f16_e32 v248, v226
	v_lshrrev_b32_e32 v249, 16, v226
	v_cvt_f32_f16_e32 v250, v227
	v_lshrrev_b32_e32 v251, 16, v227
	v_cvt_f32_f16_e32 v245, v245
	v_cvt_f32_f16_e32 v247, v247
	v_cvt_f32_f16_e32 v249, v249
	v_cvt_f32_f16_e32 v251, v251
	global_load_dwordx4 v[224:227], v[194:195], off offset:256
	v_lshl_add_u64 v[194:195], v[194:195], 0, s[12:13]
	v_fmac_f32_e32 v244, v144, v64
	v_fmac_f32_e32 v245, v145, v65
	v_fmac_f32_e32 v246, v146, v66
	v_fmac_f32_e32 v247, v147, v67
	v_fmac_f32_e32 v248, v140, v60
	v_fmac_f32_e32 v249, v141, v61
	v_fmac_f32_e32 v250, v142, v62
	v_fmac_f32_e32 v251, v143, v63
	v_cvt_f16_f32_e32 v244, v244
	v_cvt_f16_f32_e32 v245, v245
	v_cvt_f16_f32_e32 v246, v246
	v_cvt_f16_f32_e32 v247, v247
	v_cvt_f16_f32_e32 v248, v248
	v_cvt_f16_f32_e32 v249, v249
	v_cvt_f16_f32_e32 v250, v250
	v_cvt_f16_f32_e32 v251, v251
	v_and_b32_e32 v244, 0xffff, v244
	v_lshl_or_b32 v204, v245, 16, v244
	v_and_b32_e32 v246, 0xffff, v246
	v_lshl_or_b32 v205, v247, 16, v246
	v_and_b32_e32 v248, 0xffff, v248
	v_lshl_or_b32 v206, v249, 16, v248
	v_and_b32_e32 v250, 0xffff, v250
	v_lshl_or_b32 v207, v251, 16, v250
	global_store_dwordx4 v[182:183], v[204:207], off offset:256
	v_lshl_add_u64 v[182:183], v[182:183], 0, s[12:13]
	s_waitcnt vmcnt(11)
	v_cvt_f32_f16_e32 v244, v228
	v_lshrrev_b32_e32 v245, 16, v228
	v_cvt_f32_f16_e32 v246, v229
	v_lshrrev_b32_e32 v247, 16, v229
	v_cvt_f32_f16_e32 v248, v230
	v_lshrrev_b32_e32 v249, 16, v230
	v_cvt_f32_f16_e32 v250, v231
	v_lshrrev_b32_e32 v251, 16, v231
	v_cvt_f32_f16_e32 v245, v245
	v_cvt_f32_f16_e32 v247, v247
	v_cvt_f32_f16_e32 v249, v249
	v_cvt_f32_f16_e32 v251, v251
	global_load_dwordx4 v[228:231], v[194:195], off
	v_fmac_f32_e32 v244, v136, v72
	v_fmac_f32_e32 v245, v137, v73
	v_fmac_f32_e32 v246, v138, v74
	v_fmac_f32_e32 v247, v139, v75
	v_fmac_f32_e32 v248, v132, v68
	v_fmac_f32_e32 v249, v133, v69
	v_fmac_f32_e32 v250, v134, v70
	v_fmac_f32_e32 v251, v135, v71
	v_cvt_f16_f32_e32 v244, v244
	v_cvt_f16_f32_e32 v245, v245
	v_cvt_f16_f32_e32 v246, v246
	v_cvt_f16_f32_e32 v247, v247
	v_cvt_f16_f32_e32 v248, v248
	v_cvt_f16_f32_e32 v249, v249
	v_cvt_f16_f32_e32 v250, v250
	v_cvt_f16_f32_e32 v251, v251
	v_and_b32_e32 v244, 0xffff, v244
	v_lshl_or_b32 v204, v245, 16, v244
	v_and_b32_e32 v246, 0xffff, v246
	v_lshl_or_b32 v205, v247, 16, v246
	v_and_b32_e32 v248, 0xffff, v248
	v_lshl_or_b32 v206, v249, 16, v248
	v_and_b32_e32 v250, 0xffff, v250
	v_lshl_or_b32 v207, v251, 16, v250
	global_store_dwordx4 v[182:183], v[204:207], off
	s_waitcnt vmcnt(12)
	v_cvt_f32_f16_e32 v244, v232
	v_lshrrev_b32_e32 v245, 16, v232
	v_cvt_f32_f16_e32 v246, v233
	v_lshrrev_b32_e32 v247, 16, v233
	v_cvt_f32_f16_e32 v248, v234
	v_lshrrev_b32_e32 v249, 16, v234
	v_cvt_f32_f16_e32 v250, v235
	v_lshrrev_b32_e32 v251, 16, v235
	v_cvt_f32_f16_e32 v245, v245
	v_cvt_f32_f16_e32 v247, v247
	v_cvt_f32_f16_e32 v249, v249
	v_cvt_f32_f16_e32 v251, v251
	global_load_dwordx4 v[232:235], v[194:195], off offset:256
	v_lshl_add_u64 v[194:195], v[194:195], 0, s[12:13]
	v_fmac_f32_e32 v244, v128, v64
	v_fmac_f32_e32 v245, v129, v65
	v_fmac_f32_e32 v246, v130, v66
	v_fmac_f32_e32 v247, v131, v67
	v_fmac_f32_e32 v248, v124, v60
	v_fmac_f32_e32 v249, v125, v61
	v_fmac_f32_e32 v250, v126, v62
	v_fmac_f32_e32 v251, v127, v63
	v_cvt_f16_f32_e32 v244, v244
	v_cvt_f16_f32_e32 v245, v245
	v_cvt_f16_f32_e32 v246, v246
	v_cvt_f16_f32_e32 v247, v247
	v_cvt_f16_f32_e32 v248, v248
	v_cvt_f16_f32_e32 v249, v249
	v_cvt_f16_f32_e32 v250, v250
	v_cvt_f16_f32_e32 v251, v251
	v_and_b32_e32 v244, 0xffff, v244
	v_lshl_or_b32 v204, v245, 16, v244
	v_and_b32_e32 v246, 0xffff, v246
	v_lshl_or_b32 v205, v247, 16, v246
	v_and_b32_e32 v248, 0xffff, v248
	v_lshl_or_b32 v206, v249, 16, v248
	v_and_b32_e32 v250, 0xffff, v250
	v_lshl_or_b32 v207, v251, 16, v250
	global_store_dwordx4 v[182:183], v[204:207], off offset:256
	v_lshl_add_u64 v[182:183], v[182:183], 0, s[12:13]
	s_waitcnt vmcnt(13)
	v_cvt_f32_f16_e32 v244, v236
	v_lshrrev_b32_e32 v245, 16, v236
	v_cvt_f32_f16_e32 v246, v237
	v_lshrrev_b32_e32 v247, 16, v237
	v_cvt_f32_f16_e32 v248, v238
	v_lshrrev_b32_e32 v249, 16, v238
	v_cvt_f32_f16_e32 v250, v239
	v_lshrrev_b32_e32 v251, 16, v239
	v_cvt_f32_f16_e32 v245, v245
	v_cvt_f32_f16_e32 v247, v247
	v_cvt_f32_f16_e32 v249, v249
	v_cvt_f32_f16_e32 v251, v251
	global_load_dwordx4 v[236:239], v[194:195], off
	v_fmac_f32_e32 v244, v120, v72
	v_fmac_f32_e32 v245, v121, v73
	v_fmac_f32_e32 v246, v122, v74
	v_fmac_f32_e32 v247, v123, v75
	v_fmac_f32_e32 v248, v116, v68
	v_fmac_f32_e32 v249, v117, v69
	v_fmac_f32_e32 v250, v118, v70
	v_fmac_f32_e32 v251, v119, v71
	v_cvt_f16_f32_e32 v244, v244
	v_cvt_f16_f32_e32 v245, v245
	v_cvt_f16_f32_e32 v246, v246
	v_cvt_f16_f32_e32 v247, v247
	v_cvt_f16_f32_e32 v248, v248
	v_cvt_f16_f32_e32 v249, v249
	v_cvt_f16_f32_e32 v250, v250
	v_cvt_f16_f32_e32 v251, v251
	v_and_b32_e32 v244, 0xffff, v244
	v_lshl_or_b32 v204, v245, 16, v244
	v_and_b32_e32 v246, 0xffff, v246
	v_lshl_or_b32 v205, v247, 16, v246
	v_and_b32_e32 v248, 0xffff, v248
	v_lshl_or_b32 v206, v249, 16, v248
	v_and_b32_e32 v250, 0xffff, v250
	v_lshl_or_b32 v207, v251, 16, v250
	global_store_dwordx4 v[182:183], v[204:207], off
	s_waitcnt vmcnt(14)
	v_cvt_f32_f16_e32 v244, v240
	v_lshrrev_b32_e32 v245, 16, v240
	v_cvt_f32_f16_e32 v246, v241
	v_lshrrev_b32_e32 v247, 16, v241
	v_cvt_f32_f16_e32 v248, v242
	v_lshrrev_b32_e32 v249, 16, v242
	v_cvt_f32_f16_e32 v250, v243
	v_lshrrev_b32_e32 v251, 16, v243
	v_cvt_f32_f16_e32 v245, v245
	v_cvt_f32_f16_e32 v247, v247
	v_cvt_f32_f16_e32 v249, v249
	v_cvt_f32_f16_e32 v251, v251
	global_load_dwordx4 v[240:243], v[194:195], off offset:256
	v_lshl_add_u64 v[194:195], v[194:195], 0, s[12:13]
	v_fmac_f32_e32 v244, v112, v64
	v_fmac_f32_e32 v245, v113, v65
	v_fmac_f32_e32 v246, v114, v66
	v_fmac_f32_e32 v247, v115, v67
	v_fmac_f32_e32 v248, v108, v60
	v_fmac_f32_e32 v249, v109, v61
	v_fmac_f32_e32 v250, v110, v62
	v_fmac_f32_e32 v251, v111, v63
	v_cvt_f16_f32_e32 v244, v244
	v_cvt_f16_f32_e32 v245, v245
	v_cvt_f16_f32_e32 v246, v246
	v_cvt_f16_f32_e32 v247, v247
	v_cvt_f16_f32_e32 v248, v248
	v_cvt_f16_f32_e32 v249, v249
	v_cvt_f16_f32_e32 v250, v250
	v_cvt_f16_f32_e32 v251, v251
	v_and_b32_e32 v244, 0xffff, v244
	v_lshl_or_b32 v204, v245, 16, v244
	v_and_b32_e32 v246, 0xffff, v246
	v_lshl_or_b32 v205, v247, 16, v246
	v_and_b32_e32 v248, 0xffff, v248
	v_lshl_or_b32 v206, v249, 16, v248
	v_and_b32_e32 v250, 0xffff, v250
	v_lshl_or_b32 v207, v251, 16, v250
	global_store_dwordx4 v[182:183], v[204:207], off offset:256
	v_lshl_add_u64 v[182:183], v[182:183], 0, s[12:13]
	v_lshl_add_u64 v[182:183], v[182:183], 0, s[16:17]
	s_waitcnt vmcnt(15)
	v_cvt_f32_f16_e32 v244, v212
	v_lshrrev_b32_e32 v245, 16, v212
	v_cvt_f32_f16_e32 v246, v213
	v_lshrrev_b32_e32 v247, 16, v213
	v_cvt_f32_f16_e32 v248, v214
	v_lshrrev_b32_e32 v249, 16, v214
	v_cvt_f32_f16_e32 v250, v215
	v_lshrrev_b32_e32 v251, 16, v215
	v_cvt_f32_f16_e32 v245, v245
	v_cvt_f32_f16_e32 v247, v247
	v_cvt_f32_f16_e32 v249, v249
	v_cvt_f32_f16_e32 v251, v251
	v_fmac_f32_e32 v244, v104, v72
	v_fmac_f32_e32 v245, v105, v73
	v_fmac_f32_e32 v246, v106, v74
	v_fmac_f32_e32 v247, v107, v75
	v_fmac_f32_e32 v248, v100, v68
	v_fmac_f32_e32 v249, v101, v69
	v_fmac_f32_e32 v250, v102, v70
	v_fmac_f32_e32 v251, v103, v71
	v_cvt_f16_f32_e32 v244, v244
	v_cvt_f16_f32_e32 v245, v245
	v_cvt_f16_f32_e32 v246, v246
	v_cvt_f16_f32_e32 v247, v247
	v_cvt_f16_f32_e32 v248, v248
	v_cvt_f16_f32_e32 v249, v249
	v_cvt_f16_f32_e32 v250, v250
	v_cvt_f16_f32_e32 v251, v251
	v_and_b32_e32 v244, 0xffff, v244
	v_lshl_or_b32 v204, v245, 16, v244
	v_and_b32_e32 v246, 0xffff, v246
	v_lshl_or_b32 v205, v247, 16, v246
	v_and_b32_e32 v248, 0xffff, v248
	v_lshl_or_b32 v206, v249, 16, v248
	v_and_b32_e32 v250, 0xffff, v250
	v_lshl_or_b32 v207, v251, 16, v250
	global_store_dwordx4 v[182:183], v[204:207], off
	s_waitcnt vmcnt(14)
	v_cvt_f32_f16_e32 v244, v216
	v_lshrrev_b32_e32 v245, 16, v216
	v_cvt_f32_f16_e32 v246, v217
	v_lshrrev_b32_e32 v247, 16, v217
	v_cvt_f32_f16_e32 v248, v218
	v_lshrrev_b32_e32 v249, 16, v218
	v_cvt_f32_f16_e32 v250, v219
	v_lshrrev_b32_e32 v251, 16, v219
	v_cvt_f32_f16_e32 v245, v245
	v_cvt_f32_f16_e32 v247, v247
	v_cvt_f32_f16_e32 v249, v249
	v_cvt_f32_f16_e32 v251, v251
	v_fmac_f32_e32 v244, v96, v64
	v_fmac_f32_e32 v245, v97, v65
	v_fmac_f32_e32 v246, v98, v66
	v_fmac_f32_e32 v247, v99, v67
	v_fmac_f32_e32 v248, v92, v60
	v_fmac_f32_e32 v249, v93, v61
	v_fmac_f32_e32 v250, v94, v62
	v_fmac_f32_e32 v251, v95, v63
	v_cvt_f16_f32_e32 v244, v244
	v_cvt_f16_f32_e32 v245, v245
	v_cvt_f16_f32_e32 v246, v246
	v_cvt_f16_f32_e32 v247, v247
	v_cvt_f16_f32_e32 v248, v248
	v_cvt_f16_f32_e32 v249, v249
	v_cvt_f16_f32_e32 v250, v250
	v_cvt_f16_f32_e32 v251, v251
	v_and_b32_e32 v244, 0xffff, v244
	v_lshl_or_b32 v204, v245, 16, v244
	v_and_b32_e32 v246, 0xffff, v246
	v_lshl_or_b32 v205, v247, 16, v246
	v_and_b32_e32 v248, 0xffff, v248
	v_lshl_or_b32 v206, v249, 16, v248
	v_and_b32_e32 v250, 0xffff, v250
	v_lshl_or_b32 v207, v251, 16, v250
	global_store_dwordx4 v[182:183], v[204:207], off offset:256
	v_lshl_add_u64 v[182:183], v[182:183], 0, s[12:13]
	s_waitcnt vmcnt(13)
	v_cvt_f32_f16_e32 v244, v220
	v_lshrrev_b32_e32 v245, 16, v220
	v_cvt_f32_f16_e32 v246, v221
	v_lshrrev_b32_e32 v247, 16, v221
	v_cvt_f32_f16_e32 v248, v222
	v_lshrrev_b32_e32 v249, 16, v222
	v_cvt_f32_f16_e32 v250, v223
	v_lshrrev_b32_e32 v251, 16, v223
	v_cvt_f32_f16_e32 v245, v245
	v_cvt_f32_f16_e32 v247, v247
	v_cvt_f32_f16_e32 v249, v249
	v_cvt_f32_f16_e32 v251, v251
	v_fmac_f32_e32 v244, v88, v72
	v_fmac_f32_e32 v245, v89, v73
	v_fmac_f32_e32 v246, v90, v74
	v_fmac_f32_e32 v247, v91, v75
	v_fmac_f32_e32 v248, v84, v68
	v_fmac_f32_e32 v249, v85, v69
	v_fmac_f32_e32 v250, v86, v70
	v_fmac_f32_e32 v251, v87, v71
	v_cvt_f16_f32_e32 v244, v244
	v_cvt_f16_f32_e32 v245, v245
	v_cvt_f16_f32_e32 v246, v246
	v_cvt_f16_f32_e32 v247, v247
	v_cvt_f16_f32_e32 v248, v248
	v_cvt_f16_f32_e32 v249, v249
	v_cvt_f16_f32_e32 v250, v250
	v_cvt_f16_f32_e32 v251, v251
	v_and_b32_e32 v244, 0xffff, v244
	v_lshl_or_b32 v204, v245, 16, v244
	v_and_b32_e32 v246, 0xffff, v246
	v_lshl_or_b32 v205, v247, 16, v246
	v_and_b32_e32 v248, 0xffff, v248
	v_lshl_or_b32 v206, v249, 16, v248
	v_and_b32_e32 v250, 0xffff, v250
	v_lshl_or_b32 v207, v251, 16, v250
	global_store_dwordx4 v[182:183], v[204:207], off
	s_waitcnt vmcnt(12)
	v_cvt_f32_f16_e32 v244, v224
	v_lshrrev_b32_e32 v245, 16, v224
	v_cvt_f32_f16_e32 v246, v225
	v_lshrrev_b32_e32 v247, 16, v225
	v_cvt_f32_f16_e32 v248, v226
	v_lshrrev_b32_e32 v249, 16, v226
	v_cvt_f32_f16_e32 v250, v227
	v_lshrrev_b32_e32 v251, 16, v227
	v_cvt_f32_f16_e32 v245, v245
	v_cvt_f32_f16_e32 v247, v247
	v_cvt_f32_f16_e32 v249, v249
	v_cvt_f32_f16_e32 v251, v251
	v_fmac_f32_e32 v244, v80, v64
	v_fmac_f32_e32 v245, v81, v65
	v_fmac_f32_e32 v246, v82, v66
	v_fmac_f32_e32 v247, v83, v67
	v_fmac_f32_e32 v248, v76, v60
	v_fmac_f32_e32 v249, v77, v61
	v_fmac_f32_e32 v250, v78, v62
	v_fmac_f32_e32 v251, v79, v63
	v_cvt_f16_f32_e32 v244, v244
	v_cvt_f16_f32_e32 v245, v245
	v_cvt_f16_f32_e32 v246, v246
	v_cvt_f16_f32_e32 v247, v247
	v_cvt_f16_f32_e32 v248, v248
	v_cvt_f16_f32_e32 v249, v249
	v_cvt_f16_f32_e32 v250, v250
	v_cvt_f16_f32_e32 v251, v251
	v_and_b32_e32 v244, 0xffff, v244
	v_lshl_or_b32 v204, v245, 16, v244
	v_and_b32_e32 v246, 0xffff, v246
	v_lshl_or_b32 v205, v247, 16, v246
	v_and_b32_e32 v248, 0xffff, v248
	v_lshl_or_b32 v206, v249, 16, v248
	v_and_b32_e32 v250, 0xffff, v250
	v_lshl_or_b32 v207, v251, 16, v250
	global_store_dwordx4 v[182:183], v[204:207], off offset:256
	v_lshl_add_u64 v[182:183], v[182:183], 0, s[12:13]
	s_waitcnt vmcnt(11)
	v_cvt_f32_f16_e32 v244, v228
	v_lshrrev_b32_e32 v245, 16, v228
	v_cvt_f32_f16_e32 v246, v229
	v_lshrrev_b32_e32 v247, 16, v229
	v_cvt_f32_f16_e32 v248, v230
	v_lshrrev_b32_e32 v249, 16, v230
	v_cvt_f32_f16_e32 v250, v231
	v_lshrrev_b32_e32 v251, 16, v231
	v_cvt_f32_f16_e32 v245, v245
	v_cvt_f32_f16_e32 v247, v247
	v_cvt_f32_f16_e32 v249, v249
	v_cvt_f32_f16_e32 v251, v251
	v_fmac_f32_e32 v244, v56, v72
	v_fmac_f32_e32 v245, v57, v73
	v_fmac_f32_e32 v246, v58, v74
	v_fmac_f32_e32 v247, v59, v75
	v_fmac_f32_e32 v248, v52, v68
	v_fmac_f32_e32 v249, v53, v69
	v_fmac_f32_e32 v250, v54, v70
	v_fmac_f32_e32 v251, v55, v71
	v_cvt_f16_f32_e32 v244, v244
	v_cvt_f16_f32_e32 v245, v245
	v_cvt_f16_f32_e32 v246, v246
	v_cvt_f16_f32_e32 v247, v247
	v_cvt_f16_f32_e32 v248, v248
	v_cvt_f16_f32_e32 v249, v249
	v_cvt_f16_f32_e32 v250, v250
	v_cvt_f16_f32_e32 v251, v251
	v_and_b32_e32 v244, 0xffff, v244
	v_lshl_or_b32 v204, v245, 16, v244
	v_and_b32_e32 v246, 0xffff, v246
	v_lshl_or_b32 v205, v247, 16, v246
	v_and_b32_e32 v248, 0xffff, v248
	v_lshl_or_b32 v206, v249, 16, v248
	v_and_b32_e32 v250, 0xffff, v250
	v_lshl_or_b32 v207, v251, 16, v250
	global_store_dwordx4 v[182:183], v[204:207], off
	s_waitcnt vmcnt(10)
	v_cvt_f32_f16_e32 v244, v232
	v_lshrrev_b32_e32 v245, 16, v232
	v_cvt_f32_f16_e32 v246, v233
	v_lshrrev_b32_e32 v247, 16, v233
	v_cvt_f32_f16_e32 v248, v234
	v_lshrrev_b32_e32 v249, 16, v234
	v_cvt_f32_f16_e32 v250, v235
	v_lshrrev_b32_e32 v251, 16, v235
	v_cvt_f32_f16_e32 v245, v245
	v_cvt_f32_f16_e32 v247, v247
	v_cvt_f32_f16_e32 v249, v249
	v_cvt_f32_f16_e32 v251, v251
	v_fmac_f32_e32 v244, v48, v64
	v_fmac_f32_e32 v245, v49, v65
	v_fmac_f32_e32 v246, v50, v66
	v_fmac_f32_e32 v247, v51, v67
	v_fmac_f32_e32 v248, v44, v60
	v_fmac_f32_e32 v249, v45, v61
	v_fmac_f32_e32 v250, v46, v62
	v_fmac_f32_e32 v251, v47, v63
	v_cvt_f16_f32_e32 v244, v244
	v_cvt_f16_f32_e32 v245, v245
	v_cvt_f16_f32_e32 v246, v246
	v_cvt_f16_f32_e32 v247, v247
	v_cvt_f16_f32_e32 v248, v248
	v_cvt_f16_f32_e32 v249, v249
	v_cvt_f16_f32_e32 v250, v250
	v_cvt_f16_f32_e32 v251, v251
	v_and_b32_e32 v244, 0xffff, v244
	v_lshl_or_b32 v204, v245, 16, v244
	v_and_b32_e32 v246, 0xffff, v246
	v_lshl_or_b32 v205, v247, 16, v246
	v_and_b32_e32 v248, 0xffff, v248
	v_lshl_or_b32 v206, v249, 16, v248
	v_and_b32_e32 v250, 0xffff, v250
	v_lshl_or_b32 v207, v251, 16, v250
	global_store_dwordx4 v[182:183], v[204:207], off offset:256
	v_lshl_add_u64 v[182:183], v[182:183], 0, s[12:13]
	s_waitcnt vmcnt(9)
	v_cvt_f32_f16_e32 v244, v236
	v_lshrrev_b32_e32 v245, 16, v236
	v_cvt_f32_f16_e32 v246, v237
	v_lshrrev_b32_e32 v247, 16, v237
	v_cvt_f32_f16_e32 v248, v238
	v_lshrrev_b32_e32 v249, 16, v238
	v_cvt_f32_f16_e32 v250, v239
	v_lshrrev_b32_e32 v251, 16, v239
	v_cvt_f32_f16_e32 v245, v245
	v_cvt_f32_f16_e32 v247, v247
	v_cvt_f32_f16_e32 v249, v249
	v_cvt_f32_f16_e32 v251, v251
	v_fmac_f32_e32 v244, v40, v72
	v_fmac_f32_e32 v245, v41, v73
	v_fmac_f32_e32 v246, v42, v74
	v_fmac_f32_e32 v247, v43, v75
	v_fmac_f32_e32 v248, v36, v68
	v_fmac_f32_e32 v249, v37, v69
	v_fmac_f32_e32 v250, v38, v70
	v_fmac_f32_e32 v251, v39, v71
	v_cvt_f16_f32_e32 v244, v244
	v_cvt_f16_f32_e32 v245, v245
	v_cvt_f16_f32_e32 v246, v246
	v_cvt_f16_f32_e32 v247, v247
	v_cvt_f16_f32_e32 v248, v248
	v_cvt_f16_f32_e32 v249, v249
	v_cvt_f16_f32_e32 v250, v250
	v_cvt_f16_f32_e32 v251, v251
	v_and_b32_e32 v244, 0xffff, v244
	v_lshl_or_b32 v204, v245, 16, v244
	v_and_b32_e32 v246, 0xffff, v246
	v_lshl_or_b32 v205, v247, 16, v246
	v_and_b32_e32 v248, 0xffff, v248
	v_lshl_or_b32 v206, v249, 16, v248
	v_and_b32_e32 v250, 0xffff, v250
	v_lshl_or_b32 v207, v251, 16, v250
	global_store_dwordx4 v[182:183], v[204:207], off
	s_waitcnt vmcnt(8)
	v_cvt_f32_f16_e32 v244, v240
	v_lshrrev_b32_e32 v245, 16, v240
	v_cvt_f32_f16_e32 v246, v241
	v_lshrrev_b32_e32 v247, 16, v241
	v_cvt_f32_f16_e32 v248, v242
	v_lshrrev_b32_e32 v249, 16, v242
	v_cvt_f32_f16_e32 v250, v243
	v_lshrrev_b32_e32 v251, 16, v243
	v_cvt_f32_f16_e32 v245, v245
	v_cvt_f32_f16_e32 v247, v247
	v_cvt_f32_f16_e32 v249, v249
	v_cvt_f32_f16_e32 v251, v251
	v_fmac_f32_e32 v244, v32, v64
	v_fmac_f32_e32 v245, v33, v65
	v_fmac_f32_e32 v246, v34, v66
	v_fmac_f32_e32 v247, v35, v67
	v_fmac_f32_e32 v248, v28, v60
	v_fmac_f32_e32 v249, v29, v61
	v_fmac_f32_e32 v250, v30, v62
	v_fmac_f32_e32 v251, v31, v63
	v_cvt_f16_f32_e32 v244, v244
	v_cvt_f16_f32_e32 v245, v245
	v_cvt_f16_f32_e32 v246, v246
	v_cvt_f16_f32_e32 v247, v247
	v_cvt_f16_f32_e32 v248, v248
	v_cvt_f16_f32_e32 v249, v249
	v_cvt_f16_f32_e32 v250, v250
	v_cvt_f16_f32_e32 v251, v251
	v_and_b32_e32 v244, 0xffff, v244
	v_lshl_or_b32 v204, v245, 16, v244
	v_and_b32_e32 v246, 0xffff, v246
	v_lshl_or_b32 v205, v247, 16, v246
	v_and_b32_e32 v248, 0xffff, v248
	v_lshl_or_b32 v206, v249, 16, v248
	v_and_b32_e32 v250, 0xffff, v250
	v_lshl_or_b32 v207, v251, 16, v250
	global_store_dwordx4 v[182:183], v[204:207], off offset:256
	s_and_b64 vcc, exec, s[38:39]
	s_mov_b64 s[8:9], -1
	s_cbranch_vccnz .LBB0_1682
